# diff-attention P.V block: last VALU->MFMA operand wait filled with the row-sum combine instead of s_nop 1
# speedup vs baseline: 1.0094x; 1.0094x over previous
; __device__ __forceinline__ unsigned cvtpk(float lo, float hi) { f32x2_t v = {lo, hi}; bf16x2_t b = __builtin_convertvector(v, bf16x2_t); return __builtin_bit_cast(unsigned, b); }
; #define ATT_MMAG(F, dvb) do { _Pragma("unroll") for (int j = 0; j < 4; ++j) o[dvb] = __builtin_amdgcn_mfma_f32_32x32x16_bf16(F[j], pb[j >> 1][j & 1], o[dvb], 0, 0, 0); } while (0)
; template <bool DIFF> ...
;     ...
;             const float d0 = c0 - m_run, d1 = c1 - m_run;
;             float rs0 = 0.f, rs1 = 0.f;
; #pragma unroll
;             for (int r = 0; r < 16; ++r) { s0[r] = __builtin_amdgcn_exp2f(__builtin_fmaf(s0[r], sc2, d0)); s1[r] = __builtin_amdgcn_exp2f(__builtin_fmaf(s1[r], sc2, d1)); rs0 += s0[r]; rs1 += s1[r]; }
;             l_run += rs0 + rs1;
;             bf16x8 pb[2][2];
; #pragma unroll
;             for (int g = 0; g < 2; ++g) {
;                 u32x4 w0, w1;
;                 w0.x = cvtpk(s0[8 * g], s0[8 * g + 1]); w0.y = cvtpk(s0[8 * g + 2], s0[8 * g + 3]); w0.z = cvtpk(s0[8 * g + 4], s0[8 * g + 5]); w0.w = cvtpk(s0[8 * g + 6], s0[8 * g + 7]);
;                 w1.x = cvtpk(s1[8 * g], s1[8 * g + 1]); w1.y = cvtpk(s1[8 * g + 2], s1[8 * g + 3]); w1.z = cvtpk(s1[8 * g + 4], s1[8 * g + 5]); w1.w = cvtpk(s1[8 * g + 6], s1[8 * g + 7]);
;                 pb[0][g] = __builtin_bit_cast(bf16x8, w0); pb[1][g] = __builtin_bit_cast(bf16x8, w1);
;             }
;             __builtin_amdgcn_sched_barrier(0);
;             ATT_MMAG(fa, 0); ATT_LOADG(fa, 2); __builtin_amdgcn_sched_barrier(0); ATT_MMAG(fb, 1); ATT_LOADG(fb, 3); __builtin_amdgcn_sched_barrier(0); ATT_MMAG(fa, 2); ATT_MMAG(fb, 3);
.LBB0_112:
	v_sub_f32_e32 v227, v213, v209
	v_sub_f32_e32 v226, v212, v209
	v_fmamk_f32 v98, v98, 0x3e38aa3b, v226
	v_fmamk_f32 v99, v99, 0x3e38aa3b, v226
	v_fmamk_f32 v100, v100, 0x3e38aa3b, v226
	v_fmamk_f32 v101, v101, 0x3e38aa3b, v226
	v_fmamk_f32 v102, v102, 0x3e38aa3b, v226
	v_fmamk_f32 v103, v103, 0x3e38aa3b, v226
	v_fmamk_f32 v104, v104, 0x3e38aa3b, v226
	v_fmamk_f32 v105, v105, 0x3e38aa3b, v226
	v_exp_f32_e32 v98, v98
	v_exp_f32_e32 v99, v99
	v_exp_f32_e32 v100, v100
	v_exp_f32_e32 v101, v101
	v_exp_f32_e32 v102, v102
	v_exp_f32_e32 v103, v103
	v_exp_f32_e32 v104, v104
	v_exp_f32_e32 v105, v105
	v_add_f32_e32 v212, v98, v100
	v_add_f32_e32 v213, v99, v101
	v_add_f32_e32 v212, v212, v102
	v_add_f32_e32 v213, v213, v103
	v_add_f32_e32 v212, v212, v104
	v_add_f32_e32 v213, v213, v105
	v_cvt_pk_bf16_f32 v98, v98, v99
	v_cvt_pk_bf16_f32 v99, v100, v101
	v_cvt_pk_bf16_f32 v100, v102, v103
	v_cvt_pk_bf16_f32 v101, v104, v105
	s_waitcnt lgkmcnt(8)
	s_nop 1
	v_mfma_f32_32x32x16_bf16 v[50:65], v[130:133], v[98:101], v[50:65]
	v_fmamk_f32 v106, v106, 0x3e38aa3b, v226
	v_fmamk_f32 v107, v107, 0x3e38aa3b, v226
	v_fmamk_f32 v108, v108, 0x3e38aa3b, v226
	v_fmamk_f32 v109, v109, 0x3e38aa3b, v226
	v_fmamk_f32 v110, v110, 0x3e38aa3b, v226
	v_fmamk_f32 v111, v111, 0x3e38aa3b, v226
	v_fmamk_f32 v112, v112, 0x3e38aa3b, v226
	v_mfma_f32_32x32x16_bf16 v[34:49], v[134:137], v[98:101], v[34:49]
	v_fmamk_f32 v113, v113, 0x3e38aa3b, v226
	v_exp_f32_e32 v106, v106
	v_exp_f32_e32 v107, v107
	v_exp_f32_e32 v108, v108
	v_exp_f32_e32 v109, v109
	v_exp_f32_e32 v110, v110
	v_exp_f32_e32 v111, v111
	v_mfma_f32_32x32x16_bf16 v[18:33], v[138:141], v[98:101], v[18:33]
	v_exp_f32_e32 v112, v112
	v_exp_f32_e32 v113, v113
	v_add_f32_e32 v212, v212, v106
	v_add_f32_e32 v213, v213, v107
	v_add_f32_e32 v212, v212, v108
	v_add_f32_e32 v213, v213, v109
	v_add_f32_e32 v212, v212, v110
	v_add_f32_e32 v213, v213, v111
	v_add_f32_e32 v212, v212, v112
	v_add_f32_e32 v213, v213, v113
	v_cvt_pk_bf16_f32 v106, v106, v107
	v_mfma_f32_32x32x16_bf16 v[2:17], v[142:145], v[98:101], v[2:17]
	v_cvt_pk_bf16_f32 v107, v108, v109
	v_cvt_pk_bf16_f32 v108, v110, v111
	v_cvt_pk_bf16_f32 v109, v112, v113
	ds_read_b64_tr_b16 v[130:131], v228 offset:24576
	ds_read_b64_tr_b16 v[132:133], v229 offset:26624
	ds_read_b64_tr_b16 v[134:135], v230 offset:24576
	ds_read_b64_tr_b16 v[136:137], v231 offset:26624
	ds_read_b64_tr_b16 v[138:139], v232 offset:24576
	ds_read_b64_tr_b16 v[140:141], v233 offset:26624
	ds_read_b64_tr_b16 v[142:143], v234 offset:24576
	ds_read_b64_tr_b16 v[144:145], v235 offset:26624
	s_waitcnt lgkmcnt(8)
	v_mfma_f32_32x32x16_bf16 v[50:65], v[146:149], v[106:109], v[50:65]
	v_fmamk_f32 v82, v82, 0x3e38aa3b, v227
	v_fmamk_f32 v83, v83, 0x3e38aa3b, v227
	v_fmamk_f32 v84, v84, 0x3e38aa3b, v227
	v_fmamk_f32 v85, v85, 0x3e38aa3b, v227
	v_fmamk_f32 v86, v86, 0x3e38aa3b, v227
	v_fmamk_f32 v87, v87, 0x3e38aa3b, v227
	v_fmamk_f32 v88, v88, 0x3e38aa3b, v227
	v_mfma_f32_32x32x16_bf16 v[34:49], v[150:153], v[106:109], v[34:49]
	v_fmamk_f32 v89, v89, 0x3e38aa3b, v227
	v_exp_f32_e32 v82, v82
	v_exp_f32_e32 v83, v83
	v_exp_f32_e32 v84, v84
	v_exp_f32_e32 v85, v85
	v_exp_f32_e32 v86, v86
	v_exp_f32_e32 v87, v87
	v_mfma_f32_32x32x16_bf16 v[18:33], v[154:157], v[106:109], v[18:33]
	v_exp_f32_e32 v88, v88
	v_exp_f32_e32 v89, v89
	v_add_f32_e32 v212, v212, v82
	v_add_f32_e32 v213, v213, v83
	v_add_f32_e32 v212, v212, v84
	v_add_f32_e32 v213, v213, v85
	v_add_f32_e32 v212, v212, v86
	v_add_f32_e32 v213, v213, v87
	v_add_f32_e32 v212, v212, v88
	v_add_f32_e32 v213, v213, v89
	v_cvt_pk_bf16_f32 v82, v82, v83
	v_mfma_f32_32x32x16_bf16 v[2:17], v[158:161], v[106:109], v[2:17]
	v_cvt_pk_bf16_f32 v83, v84, v85
	v_cvt_pk_bf16_f32 v84, v86, v87
	v_cvt_pk_bf16_f32 v85, v88, v89
	ds_read_b64_tr_b16 v[146:147], v228 offset:28672
	ds_read_b64_tr_b16 v[148:149], v229 offset:30720
	ds_read_b64_tr_b16 v[150:151], v230 offset:28672
	ds_read_b64_tr_b16 v[152:153], v231 offset:30720
	ds_read_b64_tr_b16 v[154:155], v232 offset:28672
	ds_read_b64_tr_b16 v[156:157], v233 offset:30720
	ds_read_b64_tr_b16 v[158:159], v234 offset:28672
	ds_read_b64_tr_b16 v[160:161], v235 offset:30720
	s_waitcnt lgkmcnt(8)
	v_mfma_f32_32x32x16_bf16 v[50:65], v[130:133], v[82:85], v[50:65]
	v_fmamk_f32 v90, v90, 0x3e38aa3b, v227
	v_fmamk_f32 v91, v91, 0x3e38aa3b, v227
	v_fmamk_f32 v92, v92, 0x3e38aa3b, v227
	v_fmamk_f32 v93, v93, 0x3e38aa3b, v227
	v_fmamk_f32 v94, v94, 0x3e38aa3b, v227
	v_fmamk_f32 v95, v95, 0x3e38aa3b, v227
	v_fmamk_f32 v96, v96, 0x3e38aa3b, v227
	v_mfma_f32_32x32x16_bf16 v[34:49], v[134:137], v[82:85], v[34:49]
	v_fmamk_f32 v97, v97, 0x3e38aa3b, v227
	v_exp_f32_e32 v90, v90
	v_exp_f32_e32 v91, v91
	v_exp_f32_e32 v92, v92
	v_exp_f32_e32 v93, v93
	v_exp_f32_e32 v94, v94
	v_exp_f32_e32 v95, v95
	v_mfma_f32_32x32x16_bf16 v[18:33], v[138:141], v[82:85], v[18:33]
	v_exp_f32_e32 v96, v96
	v_exp_f32_e32 v97, v97
	v_add_f32_e32 v212, v212, v90
	v_add_f32_e32 v213, v213, v91
	v_add_f32_e32 v212, v212, v92
	v_add_f32_e32 v213, v213, v93
	v_add_f32_e32 v212, v212, v94
	v_add_f32_e32 v213, v213, v95
	v_add_f32_e32 v212, v212, v96
	v_add_f32_e32 v213, v213, v97
	v_cvt_pk_bf16_f32 v90, v90, v91
	v_mfma_f32_32x32x16_bf16 v[2:17], v[142:145], v[82:85], v[2:17]
	v_cvt_pk_bf16_f32 v91, v92, v93
	v_cvt_pk_bf16_f32 v92, v94, v95
	v_cvt_pk_bf16_f32 v93, v96, v97
	v_add_f32_e32 v212, v212, v213
	s_waitcnt lgkmcnt(0)
	v_add_f32_e32 v205, v205, v212
	v_mfma_f32_32x32x16_bf16 v[50:65], v[146:149], v[90:93], v[50:65]
	v_mfma_f32_32x32x16_bf16 v[34:49], v[150:153], v[90:93], v[34:49]
	v_mfma_f32_32x32x16_bf16 v[18:33], v[154:157], v[90:93], v[18:33]
	v_mfma_f32_32x32x16_bf16 v[2:17], v[158:161], v[90:93], v[2:17]
